# P2 slices: W_up item gains requested in one batch instead of three
# speedup vs baseline: 1.0054x; 1.0013x over previous
; #define LAS __attribute__((address_space(3)))
; __device__ __forceinline__ void p0_load(const P0Item& it, f32x4 (&w)[16], int lane) {
;     const unsigned voff = (unsigned)(((lane >> 4) * it.ldw + (lane & 15) * 4) * 4);
; #pragma unroll
;     for (int i = 0; i < 16; ++i) w[i] = __builtin_nontemporal_load((const f32x4*)((const char*)(it.src + (size_t)(4 * i) * it.ldw) + voff));
; }
; __device__ __forceinline__ void p0_finish(const P0Item& it, const f32x4 (&w)[16], LAS float* scr, int lane) {
;     const int c4 = (lane & 15) * 4, kr = lane >> 4;
;     if (it.gain) { const unsigned goff = (unsigned)(kr * 4);
; #pragma unroll
;         for (int i = 0; i < 16; ++i) { const float g = *(const float*)((const char*)(it.gain + 4 * i) + goff); *(LAS f32x4*)(scr + (kr + 4 * i) * 68 + c4) = w[i] * g; } }
; template <class F> __device__ __forceinline__ void p0_pipe(int n, F desc, LAS float* scr, int lane) {
;     P0Item a = desc(0), b = a; f32x4 w0[16], w1[16];
;     p0_load(a, w0, lane);
;     for (int j = 0; j < n; j += 2) {
;         const bool hb_ = j + 1 < n; if (hb_) { b = desc(j + 1); p0_load(b, w1, lane); }
;         p0_finish(a, w0, scr, lane);
;         if (!hb_) break;
;         if (j + 2 < n) { a = desc(j + 2); p0_load(a, w0, lane); }
;         p0_finish(b, w1, scr, lane);
.LBB0_148:
	s_add_i32 s8, s41, 0xfffff800
	s_ashr_i32 s9, s8, 31
	s_lshr_b32 s9, s9, 24
	s_add_i32 s9, s8, s9
	s_ashr_i32 s10, s9, 8
	s_and_b32 s9, s9, 0x3ffff00
	s_sub_i32 s9, s8, s9
	s_lshl_b32 s8, s10, 6
	s_lshl_b32 s10, s9, 6
	s_ashr_i32 s9, s8, 31
	s_lshl_b64 s[12:13], s[8:9], 16
	v_lshl_add_u64 v[66:67], v[138:139], 0, s[12:13]
	s_ashr_i32 s11, s10, 31
	v_lshl_add_u64 v[66:67], s[10:11], 2, v[66:67]
	v_lshl_add_u64 v[66:67], v[66:67], 0, v[140:141]
	v_add_co_u32_e32 v68, vcc, s27, v66
	s_nop 1
	v_addc_co_u32_e32 v69, vcc, 0, v67, vcc
	flat_load_dwordx4 v[126:129], v[66:67] nt
	flat_load_dwordx4 v[122:125], v[68:69] nt
	v_add_co_u32_e32 v68, vcc, s28, v66
	s_nop 1
	v_addc_co_u32_e32 v69, vcc, 0, v67, vcc
	v_add_co_u32_e32 v70, vcc, s29, v66
	s_nop 1
	v_addc_co_u32_e32 v71, vcc, 0, v67, vcc
	flat_load_dwordx4 v[118:121], v[68:69] nt
	flat_load_dwordx4 v[114:117], v[70:71] nt
	v_add_co_u32_e32 v68, vcc, s30, v66
	s_nop 1
	v_addc_co_u32_e32 v69, vcc, 0, v67, vcc
	v_add_co_u32_e32 v70, vcc, s31, v66
	s_nop 1
	v_addc_co_u32_e32 v71, vcc, 0, v67, vcc
	flat_load_dwordx4 v[110:113], v[68:69] nt
	flat_load_dwordx4 v[106:109], v[70:71] nt
	v_add_co_u32_e32 v68, vcc, s34, v66
	s_nop 1
	v_addc_co_u32_e32 v69, vcc, 0, v67, vcc
	v_add_co_u32_e32 v70, vcc, s35, v66
	s_nop 1
	v_addc_co_u32_e32 v71, vcc, 0, v67, vcc
	flat_load_dwordx4 v[102:105], v[68:69] nt
	flat_load_dwordx4 v[98:101], v[70:71] nt
	v_add_co_u32_e32 v68, vcc, s36, v66
	s_nop 1
	v_addc_co_u32_e32 v69, vcc, 0, v67, vcc
	v_add_co_u32_e32 v70, vcc, s37, v66
	s_nop 1
	v_addc_co_u32_e32 v71, vcc, 0, v67, vcc
	flat_load_dwordx4 v[94:97], v[68:69] nt
	flat_load_dwordx4 v[90:93], v[70:71] nt
	v_add_co_u32_e32 v68, vcc, s38, v66
	s_nop 1
	v_addc_co_u32_e32 v69, vcc, 0, v67, vcc
	v_add_co_u32_e32 v70, vcc, s39, v66
	s_nop 1
	v_addc_co_u32_e32 v71, vcc, 0, v67, vcc
	flat_load_dwordx4 v[86:89], v[68:69] nt
	flat_load_dwordx4 v[82:85], v[70:71] nt
	v_add_co_u32_e32 v68, vcc, s40, v66
	s_nop 1
	v_addc_co_u32_e32 v69, vcc, 0, v67, vcc
	v_add_co_u32_e32 v70, vcc, 0x340000, v66
	s_nop 1
	v_addc_co_u32_e32 v71, vcc, 0, v67, vcc
	flat_load_dwordx4 v[78:81], v[68:69] nt
	flat_load_dwordx4 v[74:77], v[70:71] nt
	v_add_co_u32_e32 v68, vcc, 0x380000, v66
	s_nop 1
	v_addc_co_u32_e32 v69, vcc, 0, v67, vcc
	v_add_co_u32_e32 v66, vcc, 0x3c0000, v66
	s_nop 1
	v_addc_co_u32_e32 v67, vcc, 0, v67, vcc
	flat_load_dwordx4 v[70:73], v[68:69] nt
	s_nop 0
	flat_load_dwordx4 v[66:69], v[66:67] nt
	v_cmp_ne_u64_e32 vcc, 0, v[148:149]
	s_and_saveexec_b64 s[12:13], vcc
	s_xor_b64 s[12:13], exec, s[12:13]
	s_cbranch_execz .LBB0_150
	v_lshl_add_u64 v[156:157], v[148:149], 0, v[136:137]
	global_load_dword v248, v[156:157], off
	global_load_dword v249, v[156:157], off offset:16
	global_load_dword v250, v[156:157], off offset:32
	global_load_dword v251, v[156:157], off offset:48
	global_load_dword v252, v[156:157], off offset:64
	global_load_dword v253, v[156:157], off offset:80
	global_load_dword v238, v[156:157], off offset:96
	global_load_dword v239, v[156:157], off offset:112
	global_load_dword v240, v[156:157], off offset:128
	global_load_dword v241, v[156:157], off offset:144
	global_load_dword v242, v[156:157], off offset:160
	global_load_dword v243, v[156:157], off offset:176
	global_load_dword v244, v[156:157], off offset:192
	global_load_dword v245, v[156:157], off offset:208
	global_load_dword v246, v[156:157], off offset:224
	global_load_dword v247, v[156:157], off offset:240
	s_waitcnt vmcnt(0) lgkmcnt(0)
	v_pk_mul_f32 v[132:133], v[4:5], v[248:249] op_sel_hi:[1,0]
	v_pk_mul_f32 v[130:131], v[2:3], v[248:249] op_sel_hi:[1,0]
	ds_write_b128 v151, v[130:133]
	s_nop 1
	v_pk_mul_f32 v[132:133], v[8:9], v[248:249] op_sel:[0,1]
	v_pk_mul_f32 v[130:131], v[6:7], v[248:249] op_sel:[0,1]
	ds_write_b128 v151, v[130:133] offset:8704
	s_nop 1
	v_pk_mul_f32 v[132:133], v[12:13], v[250:251] op_sel_hi:[1,0]
	v_pk_mul_f32 v[130:131], v[10:11], v[250:251] op_sel_hi:[1,0]
	ds_write_b128 v151, v[130:133] offset:272
	s_nop 1
	v_pk_mul_f32 v[132:133], v[16:17], v[250:251] op_sel:[0,1]
	v_pk_mul_f32 v[130:131], v[14:15], v[250:251] op_sel:[0,1]
	ds_write_b128 v151, v[130:133] offset:8976
	s_nop 1
	v_pk_mul_f32 v[132:133], v[20:21], v[252:253] op_sel_hi:[1,0]
	v_pk_mul_f32 v[130:131], v[18:19], v[252:253] op_sel_hi:[1,0]
	ds_write_b128 v151, v[130:133] offset:544
	s_nop 1
	v_pk_mul_f32 v[132:133], v[24:25], v[252:253] op_sel:[0,1]
	v_pk_mul_f32 v[130:131], v[22:23], v[252:253] op_sel:[0,1]
	ds_write_b128 v151, v[130:133] offset:9248
	s_nop 1
	v_mov_b32_e32 v248, v238
	v_mov_b32_e32 v249, v239
	v_mov_b32_e32 v250, v240
	v_mov_b32_e32 v251, v241
	v_mov_b32_e32 v252, v242
	v_mov_b32_e32 v253, v243
	v_pk_mul_f32 v[132:133], v[28:29], v[248:249] op_sel_hi:[1,0]
	v_pk_mul_f32 v[130:131], v[26:27], v[248:249] op_sel_hi:[1,0]
	ds_write_b128 v151, v[130:133] offset:816
	s_nop 1
	v_pk_mul_f32 v[132:133], v[32:33], v[248:249] op_sel:[0,1]
	v_pk_mul_f32 v[130:131], v[30:31], v[248:249] op_sel:[0,1]
	ds_write_b128 v151, v[130:133] offset:9520
	s_nop 1
	v_pk_mul_f32 v[132:133], v[36:37], v[250:251] op_sel_hi:[1,0]
	v_pk_mul_f32 v[130:131], v[34:35], v[250:251] op_sel_hi:[1,0]
	ds_write_b128 v151, v[130:133] offset:1088
	s_nop 1
	v_pk_mul_f32 v[132:133], v[40:41], v[250:251] op_sel:[0,1]
	v_pk_mul_f32 v[130:131], v[38:39], v[250:251] op_sel:[0,1]
	ds_write_b128 v151, v[130:133] offset:9792
	s_nop 1
	v_pk_mul_f32 v[132:133], v[44:45], v[252:253] op_sel_hi:[1,0]
	v_pk_mul_f32 v[130:131], v[42:43], v[252:253] op_sel_hi:[1,0]
	ds_write_b128 v151, v[130:133] offset:1360
	s_nop 1
	v_pk_mul_f32 v[132:133], v[48:49], v[252:253] op_sel:[0,1]
	v_pk_mul_f32 v[130:131], v[46:47], v[252:253] op_sel:[0,1]
	ds_write_b128 v151, v[130:133] offset:10064
	s_nop 1
	v_mov_b32_e32 v248, v244
	v_mov_b32_e32 v249, v245
	v_mov_b32_e32 v250, v246
	v_mov_b32_e32 v251, v247
	v_pk_mul_f32 v[132:133], v[52:53], v[248:249] op_sel_hi:[1,0]
	v_pk_mul_f32 v[130:131], v[50:51], v[248:249] op_sel_hi:[1,0]
	ds_write_b128 v151, v[130:133] offset:1632
	s_nop 1
	v_pk_mul_f32 v[132:133], v[56:57], v[248:249] op_sel:[0,1]
	v_pk_mul_f32 v[130:131], v[54:55], v[248:249] op_sel:[0,1]
	ds_write_b128 v151, v[130:133] offset:10336
	s_nop 1
	v_pk_mul_f32 v[132:133], v[60:61], v[250:251] op_sel_hi:[1,0]
	v_pk_mul_f32 v[130:131], v[58:59], v[250:251] op_sel_hi:[1,0]
	ds_write_b128 v151, v[130:133] offset:1904
	s_nop 1
	v_pk_mul_f32 v[132:133], v[64:65], v[250:251] op_sel:[0,1]
	v_pk_mul_f32 v[130:131], v[62:63], v[250:251] op_sel:[0,1]

; #define LAS __attribute__((address_space(3)))
; __device__ __forceinline__ void p0_finish(const P0Item& it, const f32x4 (&w)[16], LAS float* scr, int lane) {
;     const int c4 = (lane & 15) * 4, kr = lane >> 4;
;     if (it.gain) { const unsigned goff = (unsigned)(kr * 4);
; #pragma unroll
;         for (int i = 0; i < 16; ++i) { const float g = *(const float*)((const char*)(it.gain + 4 * i) + goff); *(LAS f32x4*)(scr + (kr + 4 * i) * 68 + c4) = w[i] * g; } }
.LBB0_156:
	v_lshl_add_u64 v[156:157], s[8:9], 2, v[146:147]
	global_load_dword v248, v[156:157], off
	global_load_dword v249, v[156:157], off offset:16
	global_load_dword v250, v[156:157], off offset:32
	global_load_dword v251, v[156:157], off offset:48
	global_load_dword v252, v[156:157], off offset:64
	global_load_dword v253, v[156:157], off offset:80
	global_load_dword v238, v[156:157], off offset:96
	global_load_dword v239, v[156:157], off offset:112
	global_load_dword v240, v[156:157], off offset:128
	global_load_dword v241, v[156:157], off offset:144
	global_load_dword v242, v[156:157], off offset:160
	global_load_dword v243, v[156:157], off offset:176
	global_load_dword v244, v[156:157], off offset:192
	global_load_dword v245, v[156:157], off offset:208
	global_load_dword v246, v[156:157], off offset:224
	global_load_dword v247, v[156:157], off offset:240
	s_waitcnt vmcnt(0) lgkmcnt(0)
	v_pk_mul_f32 v[128:129], v[128:129], v[248:249] op_sel_hi:[1,0]
	v_pk_mul_f32 v[126:127], v[126:127], v[248:249] op_sel_hi:[1,0]
	ds_write_b128 v151, v[126:129]
	s_nop 1
	v_pk_mul_f32 v[124:125], v[124:125], v[248:249] op_sel:[0,1]
	v_pk_mul_f32 v[122:123], v[122:123], v[248:249] op_sel:[0,1]
	ds_write_b128 v151, v[122:125] offset:8704
	s_nop 1
	v_pk_mul_f32 v[120:121], v[120:121], v[250:251] op_sel_hi:[1,0]
	v_pk_mul_f32 v[118:119], v[118:119], v[250:251] op_sel_hi:[1,0]
	ds_write_b128 v151, v[118:121] offset:272
	s_nop 1
	v_pk_mul_f32 v[116:117], v[116:117], v[250:251] op_sel:[0,1]
	v_pk_mul_f32 v[114:115], v[114:115], v[250:251] op_sel:[0,1]
	ds_write_b128 v151, v[114:117] offset:8976
	s_nop 1
	v_pk_mul_f32 v[112:113], v[112:113], v[252:253] op_sel_hi:[1,0]
	v_pk_mul_f32 v[110:111], v[110:111], v[252:253] op_sel_hi:[1,0]
	ds_write_b128 v151, v[110:113] offset:544
	s_nop 1
	v_pk_mul_f32 v[108:109], v[108:109], v[252:253] op_sel:[0,1]
	v_pk_mul_f32 v[106:107], v[106:107], v[252:253] op_sel:[0,1]
	ds_write_b128 v151, v[106:109] offset:9248
	s_nop 1
	v_mov_b32_e32 v248, v238
	v_mov_b32_e32 v249, v239
	v_mov_b32_e32 v250, v240
	v_mov_b32_e32 v251, v241
	v_mov_b32_e32 v252, v242
	v_mov_b32_e32 v253, v243
	v_pk_mul_f32 v[104:105], v[104:105], v[248:249] op_sel_hi:[1,0]
	v_pk_mul_f32 v[102:103], v[102:103], v[248:249] op_sel_hi:[1,0]
	ds_write_b128 v151, v[102:105] offset:816
	s_nop 1
	v_pk_mul_f32 v[100:101], v[100:101], v[248:249] op_sel:[0,1]
	v_pk_mul_f32 v[98:99], v[98:99], v[248:249] op_sel:[0,1]
	ds_write_b128 v151, v[98:101] offset:9520
	s_nop 1
	v_pk_mul_f32 v[96:97], v[96:97], v[250:251] op_sel_hi:[1,0]
	v_pk_mul_f32 v[94:95], v[94:95], v[250:251] op_sel_hi:[1,0]
	ds_write_b128 v151, v[94:97] offset:1088
	s_nop 1
	v_pk_mul_f32 v[92:93], v[92:93], v[250:251] op_sel:[0,1]
	v_pk_mul_f32 v[90:91], v[90:91], v[250:251] op_sel:[0,1]
	ds_write_b128 v151, v[90:93] offset:9792
	s_nop 1
	v_pk_mul_f32 v[88:89], v[88:89], v[252:253] op_sel_hi:[1,0]
	v_pk_mul_f32 v[86:87], v[86:87], v[252:253] op_sel_hi:[1,0]
	ds_write_b128 v151, v[86:89] offset:1360
	s_nop 1
	v_pk_mul_f32 v[84:85], v[84:85], v[252:253] op_sel:[0,1]
	v_pk_mul_f32 v[82:83], v[82:83], v[252:253] op_sel:[0,1]
	ds_write_b128 v151, v[82:85] offset:10064
	s_nop 1
	v_mov_b32_e32 v248, v244
	v_mov_b32_e32 v249, v245
	v_mov_b32_e32 v250, v246
	v_mov_b32_e32 v251, v247
	v_pk_mul_f32 v[80:81], v[80:81], v[248:249] op_sel_hi:[1,0]
	v_pk_mul_f32 v[78:79], v[78:79], v[248:249] op_sel_hi:[1,0]
	ds_write_b128 v151, v[78:81] offset:1632
	s_nop 1
	v_pk_mul_f32 v[76:77], v[76:77], v[248:249] op_sel:[0,1]
	v_pk_mul_f32 v[74:75], v[74:75], v[248:249] op_sel:[0,1]
	ds_write_b128 v151, v[74:77] offset:10336
	s_nop 1
	v_pk_mul_f32 v[72:73], v[72:73], v[250:251] op_sel_hi:[1,0]
	v_pk_mul_f32 v[70:71], v[70:71], v[250:251] op_sel_hi:[1,0]
	ds_write_b128 v151, v[70:73] offset:1904
	s_nop 1
	v_pk_mul_f32 v[68:69], v[68:69], v[250:251] op_sel:[0,1]
	v_pk_mul_f32 v[66:67], v[66:67], v[250:251] op_sel:[0,1]
	s_andn2_saveexec_b64 s[22:23], s[22:23]
	s_cbranch_execz .LBB0_147

; #define LAS __attribute__((address_space(3)))
; __device__ __forceinline__ void p0_load(const P0Item& it, f32x4 (&w)[16], int lane) {
;     const unsigned voff = (unsigned)(((lane >> 4) * it.ldw + (lane & 15) * 4) * 4);
; #pragma unroll
;     for (int i = 0; i < 16; ++i) w[i] = __builtin_nontemporal_load((const f32x4*)((const char*)(it.src + (size_t)(4 * i) * it.ldw) + voff));
; }
; __device__ __forceinline__ void p0_finish(const P0Item& it, const f32x4 (&w)[16], LAS float* scr, int lane) {
;     const int c4 = (lane & 15) * 4, kr = lane >> 4;
;     if (it.gain) { const unsigned goff = (unsigned)(kr * 4);
; #pragma unroll
;         for (int i = 0; i < 16; ++i) { const float g = *(const float*)((const char*)(it.gain + 4 * i) + goff); *(LAS f32x4*)(scr + (kr + 4 * i) * 68 + c4) = w[i] * g; } }
; template <class F> __device__ __forceinline__ void p0_pipe(int n, F desc, LAS float* scr, int lane) {
;     P0Item a = desc(0), b = a; f32x4 w0[16], w1[16];
;     p0_load(a, w0, lane);
;     for (int j = 0; j < n; j += 2) {
;         const bool hb_ = j + 1 < n; if (hb_) { b = desc(j + 1); p0_load(b, w1, lane); }
;         p0_finish(a, w0, scr, lane);
;         if (!hb_) break;
;         if (j + 2 < n) { a = desc(j + 2); p0_load(a, w0, lane); }
;         p0_finish(b, w1, scr, lane);
.LBB0_260:
	s_add_i32 s10, s43, 0xfffff800
	s_ashr_i32 s11, s10, 31
	s_lshr_b32 s11, s11, 24
	s_add_i32 s11, s10, s11
	s_ashr_i32 s12, s11, 8
	s_and_b32 s11, s11, 0x3ffff00
	s_sub_i32 s11, s10, s11
	s_lshl_b32 s10, s12, 6
	s_lshl_b32 s12, s11, 6
	s_ashr_i32 s11, s10, 31
	s_lshl_b64 s[22:23], s[10:11], 16
	v_lshl_add_u64 v[66:67], v[138:139], 0, s[22:23]
	s_ashr_i32 s13, s12, 31
	v_lshl_add_u64 v[66:67], s[12:13], 2, v[66:67]
	v_lshl_add_u64 v[66:67], v[66:67], 0, v[140:141]
	v_add_co_u32_e32 v68, vcc, s28, v66
	s_nop 1
	v_addc_co_u32_e32 v69, vcc, 0, v67, vcc
	flat_load_dwordx4 v[126:129], v[66:67] nt
	flat_load_dwordx4 v[122:125], v[68:69] nt
	v_add_co_u32_e32 v68, vcc, s29, v66
	s_nop 1
	v_addc_co_u32_e32 v69, vcc, 0, v67, vcc
	v_add_co_u32_e32 v70, vcc, s30, v66
	s_nop 1
	v_addc_co_u32_e32 v71, vcc, 0, v67, vcc
	flat_load_dwordx4 v[118:121], v[68:69] nt
	flat_load_dwordx4 v[114:117], v[70:71] nt
	v_add_co_u32_e32 v68, vcc, s31, v66
	s_nop 1
	v_addc_co_u32_e32 v69, vcc, 0, v67, vcc
	v_add_co_u32_e32 v70, vcc, s34, v66
	s_nop 1
	v_addc_co_u32_e32 v71, vcc, 0, v67, vcc
	flat_load_dwordx4 v[110:113], v[68:69] nt
	flat_load_dwordx4 v[106:109], v[70:71] nt
	v_add_co_u32_e32 v68, vcc, s35, v66
	s_nop 1
	v_addc_co_u32_e32 v69, vcc, 0, v67, vcc
	v_add_co_u32_e32 v70, vcc, s36, v66
	s_nop 1
	v_addc_co_u32_e32 v71, vcc, 0, v67, vcc
	flat_load_dwordx4 v[102:105], v[68:69] nt
	flat_load_dwordx4 v[98:101], v[70:71] nt
	v_add_co_u32_e32 v68, vcc, s37, v66
	s_nop 1
	v_addc_co_u32_e32 v69, vcc, 0, v67, vcc
	v_add_co_u32_e32 v70, vcc, s38, v66
	s_nop 1
	v_addc_co_u32_e32 v71, vcc, 0, v67, vcc
	flat_load_dwordx4 v[94:97], v[68:69] nt
	flat_load_dwordx4 v[90:93], v[70:71] nt
	v_add_co_u32_e32 v68, vcc, s39, v66
	s_nop 1
	v_addc_co_u32_e32 v69, vcc, 0, v67, vcc
	v_add_co_u32_e32 v70, vcc, s40, v66
	s_nop 1
	v_addc_co_u32_e32 v71, vcc, 0, v67, vcc
	flat_load_dwordx4 v[86:89], v[68:69] nt
	flat_load_dwordx4 v[82:85], v[70:71] nt
	v_add_co_u32_e32 v68, vcc, s41, v66
	s_nop 1
	v_addc_co_u32_e32 v69, vcc, 0, v67, vcc
	v_add_co_u32_e32 v70, vcc, 0x340000, v66
	s_nop 1
	v_addc_co_u32_e32 v71, vcc, 0, v67, vcc
	flat_load_dwordx4 v[78:81], v[68:69] nt
	flat_load_dwordx4 v[74:77], v[70:71] nt
	v_add_co_u32_e32 v68, vcc, 0x380000, v66
	s_nop 1
	v_addc_co_u32_e32 v69, vcc, 0, v67, vcc
	v_add_co_u32_e32 v66, vcc, 0x3c0000, v66
	s_nop 1
	v_addc_co_u32_e32 v67, vcc, 0, v67, vcc
	flat_load_dwordx4 v[70:73], v[68:69] nt
	s_nop 0
	flat_load_dwordx4 v[66:69], v[66:67] nt
	v_cmp_ne_u64_e32 vcc, 0, v[148:149]
	s_and_saveexec_b64 s[22:23], vcc
	s_xor_b64 s[22:23], exec, s[22:23]
	s_cbranch_execz .LBB0_262
	v_lshl_add_u64 v[164:165], v[148:149], 0, v[136:137]
	global_load_dword v248, v[164:165], off
	global_load_dword v249, v[164:165], off offset:16
	global_load_dword v250, v[164:165], off offset:32
	global_load_dword v251, v[164:165], off offset:48
	global_load_dword v252, v[164:165], off offset:64
	global_load_dword v253, v[164:165], off offset:80
	global_load_dword v238, v[164:165], off offset:96
	global_load_dword v239, v[164:165], off offset:112
	global_load_dword v240, v[164:165], off offset:128
	global_load_dword v241, v[164:165], off offset:144
	global_load_dword v242, v[164:165], off offset:160
	global_load_dword v243, v[164:165], off offset:176
	global_load_dword v244, v[164:165], off offset:192
	global_load_dword v245, v[164:165], off offset:208
	global_load_dword v246, v[164:165], off offset:224
	global_load_dword v247, v[164:165], off offset:240
	s_waitcnt vmcnt(0) lgkmcnt(0)
	v_pk_mul_f32 v[132:133], v[4:5], v[248:249] op_sel_hi:[1,0]
	v_pk_mul_f32 v[130:131], v[2:3], v[248:249] op_sel_hi:[1,0]
	ds_write_b128 v151, v[130:133]
	s_nop 1
	v_pk_mul_f32 v[132:133], v[8:9], v[248:249] op_sel:[0,1]
	v_pk_mul_f32 v[130:131], v[6:7], v[248:249] op_sel:[0,1]
	ds_write_b128 v151, v[130:133] offset:8704
	s_nop 1
	v_pk_mul_f32 v[132:133], v[12:13], v[250:251] op_sel_hi:[1,0]
	v_pk_mul_f32 v[130:131], v[10:11], v[250:251] op_sel_hi:[1,0]
	ds_write_b128 v151, v[130:133] offset:272
	s_nop 1
	v_pk_mul_f32 v[132:133], v[16:17], v[250:251] op_sel:[0,1]
	v_pk_mul_f32 v[130:131], v[14:15], v[250:251] op_sel:[0,1]
	ds_write_b128 v151, v[130:133] offset:8976
	s_nop 1
	v_pk_mul_f32 v[132:133], v[20:21], v[252:253] op_sel_hi:[1,0]
	v_pk_mul_f32 v[130:131], v[18:19], v[252:253] op_sel_hi:[1,0]
	ds_write_b128 v151, v[130:133] offset:544
	s_nop 1
	v_pk_mul_f32 v[132:133], v[24:25], v[252:253] op_sel:[0,1]
	v_pk_mul_f32 v[130:131], v[22:23], v[252:253] op_sel:[0,1]
	ds_write_b128 v151, v[130:133] offset:9248
	s_nop 1
	v_mov_b32_e32 v248, v238
	v_mov_b32_e32 v249, v239
	v_mov_b32_e32 v250, v240
	v_mov_b32_e32 v251, v241
	v_mov_b32_e32 v252, v242
	v_mov_b32_e32 v253, v243
	v_pk_mul_f32 v[132:133], v[28:29], v[248:249] op_sel_hi:[1,0]
	v_pk_mul_f32 v[130:131], v[26:27], v[248:249] op_sel_hi:[1,0]
	ds_write_b128 v151, v[130:133] offset:816
	s_nop 1
	v_pk_mul_f32 v[132:133], v[32:33], v[248:249] op_sel:[0,1]
	v_pk_mul_f32 v[130:131], v[30:31], v[248:249] op_sel:[0,1]
	ds_write_b128 v151, v[130:133] offset:9520
	s_nop 1
	v_pk_mul_f32 v[132:133], v[36:37], v[250:251] op_sel_hi:[1,0]
	v_pk_mul_f32 v[130:131], v[34:35], v[250:251] op_sel_hi:[1,0]
	ds_write_b128 v151, v[130:133] offset:1088
	s_nop 1
	v_pk_mul_f32 v[132:133], v[40:41], v[250:251] op_sel:[0,1]
	v_pk_mul_f32 v[130:131], v[38:39], v[250:251] op_sel:[0,1]
	ds_write_b128 v151, v[130:133] offset:9792
	s_nop 1
	v_pk_mul_f32 v[132:133], v[44:45], v[252:253] op_sel_hi:[1,0]
	v_pk_mul_f32 v[130:131], v[42:43], v[252:253] op_sel_hi:[1,0]
	ds_write_b128 v151, v[130:133] offset:1360
	s_nop 1
	v_pk_mul_f32 v[132:133], v[48:49], v[252:253] op_sel:[0,1]
	v_pk_mul_f32 v[130:131], v[46:47], v[252:253] op_sel:[0,1]
	ds_write_b128 v151, v[130:133] offset:10064
	s_nop 1
	v_mov_b32_e32 v248, v244
	v_mov_b32_e32 v249, v245
	v_mov_b32_e32 v250, v246
	v_mov_b32_e32 v251, v247
	v_pk_mul_f32 v[132:133], v[52:53], v[248:249] op_sel_hi:[1,0]
	v_pk_mul_f32 v[130:131], v[50:51], v[248:249] op_sel_hi:[1,0]
	ds_write_b128 v151, v[130:133] offset:1632
	s_nop 1
	v_pk_mul_f32 v[132:133], v[56:57], v[248:249] op_sel:[0,1]
	v_pk_mul_f32 v[130:131], v[54:55], v[248:249] op_sel:[0,1]
	ds_write_b128 v151, v[130:133] offset:10336
	s_nop 1
	v_pk_mul_f32 v[132:133], v[60:61], v[250:251] op_sel_hi:[1,0]
	v_pk_mul_f32 v[130:131], v[58:59], v[250:251] op_sel_hi:[1,0]
	ds_write_b128 v151, v[130:133] offset:1904
	s_nop 1
	v_pk_mul_f32 v[132:133], v[64:65], v[250:251] op_sel:[0,1]
	v_pk_mul_f32 v[130:131], v[62:63], v[250:251] op_sel:[0,1]

; #define LAS __attribute__((address_space(3)))
; __device__ __forceinline__ void p0_finish(const P0Item& it, const f32x4 (&w)[16], LAS float* scr, int lane) {
;     const int c4 = (lane & 15) * 4, kr = lane >> 4;
;     if (it.gain) { const unsigned goff = (unsigned)(kr * 4);
; #pragma unroll
;         for (int i = 0; i < 16; ++i) { const float g = *(const float*)((const char*)(it.gain + 4 * i) + goff); *(LAS f32x4*)(scr + (kr + 4 * i) * 68 + c4) = w[i] * g; } }
.LBB0_268:
	v_lshl_add_u64 v[164:165], s[10:11], 2, v[146:147]
	global_load_dword v248, v[164:165], off
	global_load_dword v249, v[164:165], off offset:16
	global_load_dword v250, v[164:165], off offset:32
	global_load_dword v251, v[164:165], off offset:48
	global_load_dword v252, v[164:165], off offset:64
	global_load_dword v253, v[164:165], off offset:80
	global_load_dword v238, v[164:165], off offset:96
	global_load_dword v239, v[164:165], off offset:112
	global_load_dword v240, v[164:165], off offset:128
	global_load_dword v241, v[164:165], off offset:144
	global_load_dword v242, v[164:165], off offset:160
	global_load_dword v243, v[164:165], off offset:176
	global_load_dword v244, v[164:165], off offset:192
	global_load_dword v245, v[164:165], off offset:208
	global_load_dword v246, v[164:165], off offset:224
	global_load_dword v247, v[164:165], off offset:240
	s_waitcnt vmcnt(0) lgkmcnt(0)
	v_pk_mul_f32 v[128:129], v[128:129], v[248:249] op_sel_hi:[1,0]
	v_pk_mul_f32 v[126:127], v[126:127], v[248:249] op_sel_hi:[1,0]
	ds_write_b128 v151, v[126:129]
	s_nop 1
	v_pk_mul_f32 v[124:125], v[124:125], v[248:249] op_sel:[0,1]
	v_pk_mul_f32 v[122:123], v[122:123], v[248:249] op_sel:[0,1]
	ds_write_b128 v151, v[122:125] offset:8704
	s_nop 1
	v_pk_mul_f32 v[120:121], v[120:121], v[250:251] op_sel_hi:[1,0]
	v_pk_mul_f32 v[118:119], v[118:119], v[250:251] op_sel_hi:[1,0]
	ds_write_b128 v151, v[118:121] offset:272
	s_nop 1
	v_pk_mul_f32 v[116:117], v[116:117], v[250:251] op_sel:[0,1]
	v_pk_mul_f32 v[114:115], v[114:115], v[250:251] op_sel:[0,1]
	ds_write_b128 v151, v[114:117] offset:8976
	s_nop 1
	v_pk_mul_f32 v[112:113], v[112:113], v[252:253] op_sel_hi:[1,0]
	v_pk_mul_f32 v[110:111], v[110:111], v[252:253] op_sel_hi:[1,0]
	ds_write_b128 v151, v[110:113] offset:544
	s_nop 1
	v_pk_mul_f32 v[108:109], v[108:109], v[252:253] op_sel:[0,1]
	v_pk_mul_f32 v[106:107], v[106:107], v[252:253] op_sel:[0,1]
	ds_write_b128 v151, v[106:109] offset:9248
	s_nop 1
	v_mov_b32_e32 v248, v238
	v_mov_b32_e32 v249, v239
	v_mov_b32_e32 v250, v240
	v_mov_b32_e32 v251, v241
	v_mov_b32_e32 v252, v242
	v_mov_b32_e32 v253, v243
	v_pk_mul_f32 v[104:105], v[104:105], v[248:249] op_sel_hi:[1,0]
	v_pk_mul_f32 v[102:103], v[102:103], v[248:249] op_sel_hi:[1,0]
	ds_write_b128 v151, v[102:105] offset:816
	s_nop 1
	v_pk_mul_f32 v[100:101], v[100:101], v[248:249] op_sel:[0,1]
	v_pk_mul_f32 v[98:99], v[98:99], v[248:249] op_sel:[0,1]
	ds_write_b128 v151, v[98:101] offset:9520
	s_nop 1
	v_pk_mul_f32 v[96:97], v[96:97], v[250:251] op_sel_hi:[1,0]
	v_pk_mul_f32 v[94:95], v[94:95], v[250:251] op_sel_hi:[1,0]
	ds_write_b128 v151, v[94:97] offset:1088
	s_nop 1
	v_pk_mul_f32 v[92:93], v[92:93], v[250:251] op_sel:[0,1]
	v_pk_mul_f32 v[90:91], v[90:91], v[250:251] op_sel:[0,1]
	ds_write_b128 v151, v[90:93] offset:9792
	s_nop 1
	v_pk_mul_f32 v[88:89], v[88:89], v[252:253] op_sel_hi:[1,0]
	v_pk_mul_f32 v[86:87], v[86:87], v[252:253] op_sel_hi:[1,0]
	ds_write_b128 v151, v[86:89] offset:1360
	s_nop 1
	v_pk_mul_f32 v[84:85], v[84:85], v[252:253] op_sel:[0,1]
	v_pk_mul_f32 v[82:83], v[82:83], v[252:253] op_sel:[0,1]
	ds_write_b128 v151, v[82:85] offset:10064
	s_nop 1
	v_mov_b32_e32 v248, v244
	v_mov_b32_e32 v249, v245
	v_mov_b32_e32 v250, v246
	v_mov_b32_e32 v251, v247
	v_pk_mul_f32 v[80:81], v[80:81], v[248:249] op_sel_hi:[1,0]
	v_pk_mul_f32 v[78:79], v[78:79], v[248:249] op_sel_hi:[1,0]
	ds_write_b128 v151, v[78:81] offset:1632
	s_nop 1
	v_pk_mul_f32 v[76:77], v[76:77], v[248:249] op_sel:[0,1]
	v_pk_mul_f32 v[74:75], v[74:75], v[248:249] op_sel:[0,1]
	ds_write_b128 v151, v[74:77] offset:10336
	s_nop 1
	v_pk_mul_f32 v[72:73], v[72:73], v[250:251] op_sel_hi:[1,0]
	v_pk_mul_f32 v[70:71], v[70:71], v[250:251] op_sel_hi:[1,0]
	ds_write_b128 v151, v[70:73] offset:1904
	s_nop 1
	v_pk_mul_f32 v[68:69], v[68:69], v[250:251] op_sel:[0,1]
	v_pk_mul_f32 v[66:67], v[66:67], v[250:251] op_sel:[0,1]
	s_andn2_saveexec_b64 s[24:25], s[24:25]
	s_cbranch_execz .LBB0_259

; #define LAS __attribute__((address_space(3)))
; __device__ __forceinline__ void p0_load(const P0Item& it, f32x4 (&w)[16], int lane) {
;     const unsigned voff = (unsigned)(((lane >> 4) * it.ldw + (lane & 15) * 4) * 4);
; #pragma unroll
;     for (int i = 0; i < 16; ++i) w[i] = __builtin_nontemporal_load((const f32x4*)((const char*)(it.src + (size_t)(4 * i) * it.ldw) + voff));
; }
; __device__ __forceinline__ void p0_finish(const P0Item& it, const f32x4 (&w)[16], LAS float* scr, int lane) {
;     const int c4 = (lane & 15) * 4, kr = lane >> 4;
;     if (it.gain) { const unsigned goff = (unsigned)(kr * 4);
; #pragma unroll
;         for (int i = 0; i < 16; ++i) { const float g = *(const float*)((const char*)(it.gain + 4 * i) + goff); *(LAS f32x4*)(scr + (kr + 4 * i) * 68 + c4) = w[i] * g; } }
; template <class F> __device__ __forceinline__ void p0_pipe(int n, F desc, LAS float* scr, int lane) {
;     P0Item a = desc(0), b = a; f32x4 w0[16], w1[16];
;     p0_load(a, w0, lane);
;     for (int j = 0; j < n; j += 2) {
;         const bool hb_ = j + 1 < n; if (hb_) { b = desc(j + 1); p0_load(b, w1, lane); }
;         p0_finish(a, w0, scr, lane);
;         if (!hb_) break;
;         if (j + 2 < n) { a = desc(j + 2); p0_load(a, w0, lane); }
;         p0_finish(b, w1, scr, lane);
.LBB0_458:
	s_add_i32 s8, s41, 0xfffff800
	s_ashr_i32 s9, s8, 31
	s_lshr_b32 s9, s9, 24
	s_add_i32 s9, s8, s9
	s_ashr_i32 s10, s9, 8
	s_and_b32 s9, s9, 0x3ffff00
	s_sub_i32 s9, s8, s9
	s_lshl_b32 s8, s10, 6
	s_lshl_b32 s10, s9, 6
	s_ashr_i32 s9, s8, 31
	s_lshl_b64 s[12:13], s[8:9], 16
	v_lshl_add_u64 v[66:67], v[138:139], 0, s[12:13]
	s_ashr_i32 s11, s10, 31
	v_lshl_add_u64 v[66:67], s[10:11], 2, v[66:67]
	v_lshl_add_u64 v[66:67], v[66:67], 0, v[140:141]
	v_add_co_u32_e32 v68, vcc, s26, v66
	s_nop 1
	v_addc_co_u32_e32 v69, vcc, 0, v67, vcc
	flat_load_dwordx4 v[126:129], v[66:67] nt
	flat_load_dwordx4 v[122:125], v[68:69] nt
	v_add_co_u32_e32 v68, vcc, s27, v66
	s_nop 1
	v_addc_co_u32_e32 v69, vcc, 0, v67, vcc
	v_add_co_u32_e32 v70, vcc, s28, v66
	s_nop 1
	v_addc_co_u32_e32 v71, vcc, 0, v67, vcc
	flat_load_dwordx4 v[118:121], v[68:69] nt
	flat_load_dwordx4 v[114:117], v[70:71] nt
	v_add_co_u32_e32 v68, vcc, s29, v66
	s_nop 1
	v_addc_co_u32_e32 v69, vcc, 0, v67, vcc
	v_add_co_u32_e32 v70, vcc, s30, v66
	s_nop 1
	v_addc_co_u32_e32 v71, vcc, 0, v67, vcc
	flat_load_dwordx4 v[110:113], v[68:69] nt
	flat_load_dwordx4 v[106:109], v[70:71] nt
	v_add_co_u32_e32 v68, vcc, s31, v66
	s_nop 1
	v_addc_co_u32_e32 v69, vcc, 0, v67, vcc
	v_add_co_u32_e32 v70, vcc, s34, v66
	s_nop 1
	v_addc_co_u32_e32 v71, vcc, 0, v67, vcc
	flat_load_dwordx4 v[102:105], v[68:69] nt
	flat_load_dwordx4 v[98:101], v[70:71] nt
	v_add_co_u32_e32 v68, vcc, s35, v66
	s_nop 1
	v_addc_co_u32_e32 v69, vcc, 0, v67, vcc
	v_add_co_u32_e32 v70, vcc, s36, v66
	s_nop 1
	v_addc_co_u32_e32 v71, vcc, 0, v67, vcc
	flat_load_dwordx4 v[94:97], v[68:69] nt
	flat_load_dwordx4 v[90:93], v[70:71] nt
	v_add_co_u32_e32 v68, vcc, s37, v66
	s_nop 1
	v_addc_co_u32_e32 v69, vcc, 0, v67, vcc
	v_add_co_u32_e32 v70, vcc, s38, v66
	s_nop 1
	v_addc_co_u32_e32 v71, vcc, 0, v67, vcc
	flat_load_dwordx4 v[86:89], v[68:69] nt
	flat_load_dwordx4 v[82:85], v[70:71] nt
	v_add_co_u32_e32 v68, vcc, s39, v66
	s_nop 1
	v_addc_co_u32_e32 v69, vcc, 0, v67, vcc
	v_add_co_u32_e32 v70, vcc, 0x340000, v66
	s_nop 1
	v_addc_co_u32_e32 v71, vcc, 0, v67, vcc
	flat_load_dwordx4 v[78:81], v[68:69] nt
	flat_load_dwordx4 v[74:77], v[70:71] nt
	v_add_co_u32_e32 v68, vcc, 0x380000, v66
	s_nop 1
	v_addc_co_u32_e32 v69, vcc, 0, v67, vcc
	v_add_co_u32_e32 v66, vcc, 0x3c0000, v66
	s_nop 1
	v_addc_co_u32_e32 v67, vcc, 0, v67, vcc
	flat_load_dwordx4 v[70:73], v[68:69] nt
	s_nop 0
	flat_load_dwordx4 v[66:69], v[66:67] nt
	v_cmp_ne_u64_e32 vcc, 0, v[148:149]
	s_and_saveexec_b64 s[12:13], vcc
	s_xor_b64 s[12:13], exec, s[12:13]
	s_cbranch_execz .LBB0_460
	v_lshl_add_u64 v[156:157], v[148:149], 0, v[136:137]
	global_load_dword v248, v[156:157], off
	global_load_dword v249, v[156:157], off offset:16
	global_load_dword v250, v[156:157], off offset:32
	global_load_dword v251, v[156:157], off offset:48
	global_load_dword v252, v[156:157], off offset:64
	global_load_dword v253, v[156:157], off offset:80
	global_load_dword v238, v[156:157], off offset:96
	global_load_dword v239, v[156:157], off offset:112
	global_load_dword v240, v[156:157], off offset:128
	global_load_dword v241, v[156:157], off offset:144
	global_load_dword v242, v[156:157], off offset:160
	global_load_dword v243, v[156:157], off offset:176
	global_load_dword v244, v[156:157], off offset:192
	global_load_dword v245, v[156:157], off offset:208
	global_load_dword v246, v[156:157], off offset:224
	global_load_dword v247, v[156:157], off offset:240
	s_waitcnt vmcnt(0) lgkmcnt(0)
	v_pk_mul_f32 v[132:133], v[4:5], v[248:249] op_sel_hi:[1,0]
	v_pk_mul_f32 v[130:131], v[2:3], v[248:249] op_sel_hi:[1,0]
	ds_write_b128 v151, v[130:133]
	s_nop 1
	v_pk_mul_f32 v[132:133], v[8:9], v[248:249] op_sel:[0,1]
	v_pk_mul_f32 v[130:131], v[6:7], v[248:249] op_sel:[0,1]
	ds_write_b128 v151, v[130:133] offset:8704
	s_nop 1
	v_pk_mul_f32 v[132:133], v[12:13], v[250:251] op_sel_hi:[1,0]
	v_pk_mul_f32 v[130:131], v[10:11], v[250:251] op_sel_hi:[1,0]
	ds_write_b128 v151, v[130:133] offset:272
	s_nop 1
	v_pk_mul_f32 v[132:133], v[16:17], v[250:251] op_sel:[0,1]
	v_pk_mul_f32 v[130:131], v[14:15], v[250:251] op_sel:[0,1]
	ds_write_b128 v151, v[130:133] offset:8976
	s_nop 1
	v_pk_mul_f32 v[132:133], v[20:21], v[252:253] op_sel_hi:[1,0]
	v_pk_mul_f32 v[130:131], v[18:19], v[252:253] op_sel_hi:[1,0]
	ds_write_b128 v151, v[130:133] offset:544
	s_nop 1
	v_pk_mul_f32 v[132:133], v[24:25], v[252:253] op_sel:[0,1]
	v_pk_mul_f32 v[130:131], v[22:23], v[252:253] op_sel:[0,1]
	ds_write_b128 v151, v[130:133] offset:9248
	s_nop 1
	v_mov_b32_e32 v248, v238
	v_mov_b32_e32 v249, v239
	v_mov_b32_e32 v250, v240
	v_mov_b32_e32 v251, v241
	v_mov_b32_e32 v252, v242
	v_mov_b32_e32 v253, v243
	v_pk_mul_f32 v[132:133], v[28:29], v[248:249] op_sel_hi:[1,0]
	v_pk_mul_f32 v[130:131], v[26:27], v[248:249] op_sel_hi:[1,0]
	ds_write_b128 v151, v[130:133] offset:816
	s_nop 1
	v_pk_mul_f32 v[132:133], v[32:33], v[248:249] op_sel:[0,1]
	v_pk_mul_f32 v[130:131], v[30:31], v[248:249] op_sel:[0,1]
	ds_write_b128 v151, v[130:133] offset:9520
	s_nop 1
	v_pk_mul_f32 v[132:133], v[36:37], v[250:251] op_sel_hi:[1,0]
	v_pk_mul_f32 v[130:131], v[34:35], v[250:251] op_sel_hi:[1,0]
	ds_write_b128 v151, v[130:133] offset:1088
	s_nop 1
	v_pk_mul_f32 v[132:133], v[40:41], v[250:251] op_sel:[0,1]
	v_pk_mul_f32 v[130:131], v[38:39], v[250:251] op_sel:[0,1]
	ds_write_b128 v151, v[130:133] offset:9792
	s_nop 1
	v_pk_mul_f32 v[132:133], v[44:45], v[252:253] op_sel_hi:[1,0]
	v_pk_mul_f32 v[130:131], v[42:43], v[252:253] op_sel_hi:[1,0]
	ds_write_b128 v151, v[130:133] offset:1360
	s_nop 1
	v_pk_mul_f32 v[132:133], v[48:49], v[252:253] op_sel:[0,1]
	v_pk_mul_f32 v[130:131], v[46:47], v[252:253] op_sel:[0,1]
	ds_write_b128 v151, v[130:133] offset:10064
	s_nop 1
	v_mov_b32_e32 v248, v244
	v_mov_b32_e32 v249, v245
	v_mov_b32_e32 v250, v246
	v_mov_b32_e32 v251, v247
	v_pk_mul_f32 v[132:133], v[52:53], v[248:249] op_sel_hi:[1,0]
	v_pk_mul_f32 v[130:131], v[50:51], v[248:249] op_sel_hi:[1,0]
	ds_write_b128 v151, v[130:133] offset:1632
	s_nop 1
	v_pk_mul_f32 v[132:133], v[56:57], v[248:249] op_sel:[0,1]
	v_pk_mul_f32 v[130:131], v[54:55], v[248:249] op_sel:[0,1]
	ds_write_b128 v151, v[130:133] offset:10336
	s_nop 1
	v_pk_mul_f32 v[132:133], v[60:61], v[250:251] op_sel_hi:[1,0]
	v_pk_mul_f32 v[130:131], v[58:59], v[250:251] op_sel_hi:[1,0]
	ds_write_b128 v151, v[130:133] offset:1904
	s_nop 1
	v_pk_mul_f32 v[132:133], v[64:65], v[250:251] op_sel:[0,1]
	v_pk_mul_f32 v[130:131], v[62:63], v[250:251] op_sel:[0,1]
